# v66 + split-K slab stores staged via LDS into full 512B-row pieces (G2/G4 sub-unit epilogues)
# speedup vs baseline: 1.0025x; 1.0025x over previous
; template <class Epi, bool ALIGN_EPI = true>
; __device__ __forceinline__ void gemm_phase(LAS unsigned char* lds, const Gemm g, const Order& S, const Epi& E) {
;     ...
;         else {
;             float* sl = g.slab + (size_t)(cur.slot * cur.S + cur.ks) * 65536 + (size_t)(wr * 64 + fr) * 256 + wc * 32 + 8 * fq;
; #pragma unroll
;             for (int ai = 0; ai < 2; ++ai)
; #pragma unroll
;                 for (int m = 0; m < 4; ++m)
; #pragma unroll
;                     for (int bj = 0; bj < 2; ++bj)
; #pragma unroll
;                         for (int n = 0; n < 2; ++n) *(f32x4*)(sl + (size_t)(ai * HALF + m * 16) * 256 + bj * HALF + 4 * n) = acc[ai][bj][m][n];
;         }
.LBB0_245:
	v_readlane_b32 s92, v254, 57
	s_cmp_lg_u32 s35, 0
	v_readlane_b32 s93, v254, 58
	s_mov_b32 s65, s43
	s_cbranch_scc0 .LBB0_247
	s_mul_i32 s34, s35, s34
	s_add_i32 s64, s34, s87
	s_lshl_b64 s[34:35], s[64:65], 18
	v_lshl_add_u64 v[62:63], v[214:215], 0, s[34:35]
	v_and_b32_e32 v74, 15, v0
	v_bfe_u32 v75, v0, 4, 2
	v_lshrrev_b32_e32 v76, 6, v0
	v_and_b32_e32 v77, 3, v76
	v_lshrrev_b32_e32 v76, 2, v76
	v_lshlrev_b32_e32 v78, 16, v76
	v_lshl_add_u32 v78, v74, 10, v78
	v_lshl_add_u32 v78, v77, 7, v78
	v_lshl_add_u32 v78, v75, 5, v78
	v_sub_co_u32_e32 v80, vcc, v62, v78
	v_subbrev_co_u32_e32 v81, vcc, 0, v63, vcc
	v_readfirstlane_b32 s98, v80
	v_readfirstlane_b32 s99, v81
	v_mul_u32_u24_e32 v79, 0x2100, v76
	v_add_u32_e32 v79, 0x20000, v79
	v_mul_u32_u24_e32 v82, 0x210, v74
	v_lshl_add_u32 v82, v77, 7, v82
	v_lshl_add_u32 v82, v75, 5, v82
	v_add_u32_e32 v86, v79, v82
	v_bfe_u32 v83, v0, 5, 1
	v_lshl_add_u32 v83, v77, 2, v83
	v_and_b32_e32 v84, 31, v0
	v_lshlrev_b32_e32 v84, 4, v84
	v_mul_u32_u24_e32 v85, 0x210, v83
	v_add3_u32 v87, v79, v85, v84
	v_lshl_add_u32 v83, v76, 6, v83
	v_lshl_add_u32 v88, v83, 10, v84
	ds_write_b128 v86, v[174:177]
	ds_write_b128 v86, v[170:173] offset:16
	s_waitcnt lgkmcnt(0)
	s_barrier
	ds_read_b128 v[92:95], v87
	ds_read_b128 v[96:99], v87 offset:1056
	v_add_u32_e32 v89, 0x0, v88
	v_add_u32_e32 v90, 0x800, v88
	s_waitcnt lgkmcnt(1)
	global_store_dwordx4 v89, v[92:95], s[98:99]
	s_waitcnt lgkmcnt(0)
	global_store_dwordx4 v90, v[96:99], s[98:99]
	s_barrier
	ds_write_b128 v86, v[166:169]
	ds_write_b128 v86, v[162:165] offset:16
	s_waitcnt lgkmcnt(0)
	s_barrier
	ds_read_b128 v[92:95], v87
	ds_read_b128 v[96:99], v87 offset:1056
	v_add_u32_e32 v89, 0x200, v88
	v_add_u32_e32 v90, 0xa00, v88
	s_waitcnt lgkmcnt(1)
	global_store_dwordx4 v89, v[92:95], s[98:99]
	s_waitcnt lgkmcnt(0)
	global_store_dwordx4 v90, v[96:99], s[98:99]
	s_barrier
	ds_write_b128 v86, v[158:161]
	ds_write_b128 v86, v[154:157] offset:16
	s_waitcnt lgkmcnt(0)
	s_barrier
	ds_read_b128 v[92:95], v87
	ds_read_b128 v[96:99], v87 offset:1056
	v_add_u32_e32 v89, 0x4000, v88
	v_add_u32_e32 v90, 0x4800, v88
	s_waitcnt lgkmcnt(1)
	global_store_dwordx4 v89, v[92:95], s[98:99]
	s_waitcnt lgkmcnt(0)
	global_store_dwordx4 v90, v[96:99], s[98:99]
	s_barrier
	ds_write_b128 v86, v[150:153]
	ds_write_b128 v86, v[146:149] offset:16
	s_waitcnt lgkmcnt(0)
	s_barrier
	ds_read_b128 v[92:95], v87
	ds_read_b128 v[96:99], v87 offset:1056
	v_add_u32_e32 v89, 0x4200, v88
	v_add_u32_e32 v90, 0x4a00, v88
	s_waitcnt lgkmcnt(1)
	global_store_dwordx4 v89, v[92:95], s[98:99]
	s_waitcnt lgkmcnt(0)
	global_store_dwordx4 v90, v[96:99], s[98:99]
	s_barrier
	ds_write_b128 v86, v[142:145]
	ds_write_b128 v86, v[138:141] offset:16
	s_waitcnt lgkmcnt(0)
	s_barrier
	ds_read_b128 v[92:95], v87
	ds_read_b128 v[96:99], v87 offset:1056
	v_add_u32_e32 v89, 0x8000, v88
	v_add_u32_e32 v90, 0x8800, v88
	s_waitcnt lgkmcnt(1)
	global_store_dwordx4 v89, v[92:95], s[98:99]
	s_waitcnt lgkmcnt(0)
	global_store_dwordx4 v90, v[96:99], s[98:99]
	s_barrier
	ds_write_b128 v86, v[134:137]
	ds_write_b128 v86, v[130:133] offset:16
	s_waitcnt lgkmcnt(0)
	s_barrier
	ds_read_b128 v[92:95], v87
	ds_read_b128 v[96:99], v87 offset:1056
	v_add_u32_e32 v89, 0x8200, v88
	v_add_u32_e32 v90, 0x8a00, v88
	s_waitcnt lgkmcnt(1)
	global_store_dwordx4 v89, v[92:95], s[98:99]
	s_waitcnt lgkmcnt(0)
	global_store_dwordx4 v90, v[96:99], s[98:99]
	s_barrier
	ds_write_b128 v86, v[126:129]
	ds_write_b128 v86, v[122:125] offset:16
	s_waitcnt lgkmcnt(0)
	s_barrier
	ds_read_b128 v[92:95], v87
	ds_read_b128 v[96:99], v87 offset:1056
	v_add_u32_e32 v89, 0xc000, v88
	v_add_u32_e32 v90, 0xc800, v88
	s_waitcnt lgkmcnt(1)
	global_store_dwordx4 v89, v[92:95], s[98:99]
	s_waitcnt lgkmcnt(0)
	global_store_dwordx4 v90, v[96:99], s[98:99]
	s_barrier
; template <class Epi, bool ALIGN_EPI = true>
; __device__ __forceinline__ void gemm_phase(LAS unsigned char* lds, const Gemm g, const Order& S, const Epi& E) {
;     ...
;         else {
;             float* sl = g.slab + (size_t)(cur.slot * cur.S + cur.ks) * 65536 + (size_t)(wr * 64 + fr) * 256 + wc * 32 + 8 * fq;
; #pragma unroll
;             for (int ai = 0; ai < 2; ++ai)
; #pragma unroll
;                 for (int m = 0; m < 4; ++m)
; #pragma unroll
;                     for (int bj = 0; bj < 2; ++bj)
; #pragma unroll
;                         for (int n = 0; n < 2; ++n) *(f32x4*)(sl + (size_t)(ai * HALF + m * 16) * 256 + bj * HALF + 4 * n) = acc[ai][bj][m][n];
;         }
	ds_write_b128 v86, v[118:121]
	ds_write_b128 v86, v[114:117] offset:16
	s_waitcnt lgkmcnt(0)
	s_barrier
	ds_read_b128 v[92:95], v87
	ds_read_b128 v[96:99], v87 offset:1056
	v_add_u32_e32 v89, 0xc200, v88
	v_add_u32_e32 v90, 0xca00, v88
	s_waitcnt lgkmcnt(1)
	global_store_dwordx4 v89, v[92:95], s[98:99]
	s_waitcnt lgkmcnt(0)
	global_store_dwordx4 v90, v[96:99], s[98:99]
	s_barrier
	ds_write_b128 v86, v[70:73]
	ds_write_b128 v86, v[58:61] offset:16
	s_waitcnt lgkmcnt(0)
	s_barrier
	ds_read_b128 v[92:95], v87
	ds_read_b128 v[96:99], v87 offset:1056
	v_add_u32_e32 v89, 0x20000, v88
	v_add_u32_e32 v90, 0x20800, v88
	s_waitcnt lgkmcnt(1)
	global_store_dwordx4 v89, v[92:95], s[98:99]
	s_waitcnt lgkmcnt(0)
	global_store_dwordx4 v90, v[96:99], s[98:99]
	s_barrier
	ds_write_b128 v86, v[54:57]
	ds_write_b128 v86, v[50:53] offset:16
	s_waitcnt lgkmcnt(0)
	s_barrier
	ds_read_b128 v[92:95], v87
	ds_read_b128 v[96:99], v87 offset:1056
	v_add_u32_e32 v89, 0x20200, v88
	v_add_u32_e32 v90, 0x20a00, v88
	s_waitcnt lgkmcnt(1)
	global_store_dwordx4 v89, v[92:95], s[98:99]
	s_waitcnt lgkmcnt(0)
	global_store_dwordx4 v90, v[96:99], s[98:99]
	s_barrier
	ds_write_b128 v86, v[46:49]
	ds_write_b128 v86, v[42:45] offset:16
	s_waitcnt lgkmcnt(0)
	s_barrier
	ds_read_b128 v[92:95], v87
	ds_read_b128 v[96:99], v87 offset:1056
	v_add_u32_e32 v89, 0x24000, v88
	v_add_u32_e32 v90, 0x24800, v88
	s_waitcnt lgkmcnt(1)
	global_store_dwordx4 v89, v[92:95], s[98:99]
	s_waitcnt lgkmcnt(0)
	global_store_dwordx4 v90, v[96:99], s[98:99]
	s_barrier
	ds_write_b128 v86, v[38:41]
	ds_write_b128 v86, v[34:37] offset:16
	s_waitcnt lgkmcnt(0)
	s_barrier
	ds_read_b128 v[92:95], v87
	ds_read_b128 v[96:99], v87 offset:1056
	v_add_u32_e32 v89, 0x24200, v88
	v_add_u32_e32 v90, 0x24a00, v88
	s_waitcnt lgkmcnt(1)
	global_store_dwordx4 v89, v[92:95], s[98:99]
	s_waitcnt lgkmcnt(0)
	global_store_dwordx4 v90, v[96:99], s[98:99]
	s_barrier
	ds_write_b128 v86, v[30:33]
	ds_write_b128 v86, v[26:29] offset:16
	s_waitcnt lgkmcnt(0)
	s_barrier
	ds_read_b128 v[92:95], v87
	ds_read_b128 v[96:99], v87 offset:1056
	v_add_u32_e32 v89, 0x28000, v88
	v_add_u32_e32 v90, 0x28800, v88
	s_waitcnt lgkmcnt(1)
	global_store_dwordx4 v89, v[92:95], s[98:99]
	s_waitcnt lgkmcnt(0)
	global_store_dwordx4 v90, v[96:99], s[98:99]
	s_barrier
	ds_write_b128 v86, v[22:25]
	ds_write_b128 v86, v[18:21] offset:16
	s_waitcnt lgkmcnt(0)
	s_barrier
	ds_read_b128 v[92:95], v87
	ds_read_b128 v[96:99], v87 offset:1056
	v_add_u32_e32 v89, 0x28200, v88
	v_add_u32_e32 v90, 0x28a00, v88
	s_waitcnt lgkmcnt(1)
	global_store_dwordx4 v89, v[92:95], s[98:99]
	s_waitcnt lgkmcnt(0)
	global_store_dwordx4 v90, v[96:99], s[98:99]
	s_barrier
	ds_write_b128 v86, v[14:17]
	ds_write_b128 v86, v[10:13] offset:16
	s_waitcnt lgkmcnt(0)
	s_barrier
	ds_read_b128 v[92:95], v87
	ds_read_b128 v[96:99], v87 offset:1056
	v_add_u32_e32 v89, 0x2c000, v88
	v_add_u32_e32 v90, 0x2c800, v88
	s_waitcnt lgkmcnt(1)
	global_store_dwordx4 v89, v[92:95], s[98:99]
	s_waitcnt lgkmcnt(0)
	global_store_dwordx4 v90, v[96:99], s[98:99]
	s_barrier
	ds_write_b128 v86, v[6:9]
	ds_write_b128 v86, v[2:5] offset:16
	s_waitcnt lgkmcnt(0)
	s_barrier
	ds_read_b128 v[92:95], v87
	ds_read_b128 v[96:99], v87 offset:1056
	v_add_u32_e32 v89, 0x2c200, v88
	v_add_u32_e32 v90, 0x2ca00, v88
	s_waitcnt lgkmcnt(1)
	global_store_dwordx4 v89, v[92:95], s[98:99]
	s_waitcnt lgkmcnt(0)
	global_store_dwordx4 v90, v[96:99], s[98:99]
	s_barrier
	s_mov_b32 s28, 0xc000
	s_mov_b32 s28, 0x20000
	s_mov_b32 s28, 0x24000
	s_mov_b64 s[58:59], 0
	s_branch .LBB0_248

; template <class Epi, bool ALIGN_EPI = true>
; __device__ __forceinline__ void gemm_phase(LAS unsigned char* lds, const Gemm g, const Order& S, const Epi& E) {
;     ...
;         else {
;             float* sl = g.slab + (size_t)(cur.slot * cur.S + cur.ks) * 65536 + (size_t)(wr * 64 + fr) * 256 + wc * 32 + 8 * fq;
; #pragma unroll
;             for (int ai = 0; ai < 2; ++ai)
; #pragma unroll
;                 for (int m = 0; m < 4; ++m)
; #pragma unroll
;                     for (int bj = 0; bj < 2; ++bj)
; #pragma unroll
;                         for (int n = 0; n < 2; ++n) *(f32x4*)(sl + (size_t)(ai * HALF + m * 16) * 256 + bj * HALF + 4 * n) = acc[ai][bj][m][n];
;         }
.LBB0_377:
	v_readlane_b32 s92, v254, 57
	s_cmp_lg_u32 s35, 0
	v_readlane_b32 s93, v254, 58
	s_mov_b32 s63, s43
	v_readlane_b32 s90, v255, 22
	s_cbranch_scc0 .LBB0_396
	s_mul_i32 s34, s35, s34
	s_add_i32 s62, s34, s85
	s_lshl_b64 s[34:35], s[62:63], 18
	v_lshl_add_u64 v[62:63], v[214:215], 0, s[34:35]
	v_and_b32_e32 v74, 15, v0
	v_bfe_u32 v75, v0, 4, 2
	v_lshrrev_b32_e32 v76, 6, v0
	v_and_b32_e32 v77, 3, v76
	v_lshrrev_b32_e32 v76, 2, v76
	v_lshlrev_b32_e32 v78, 16, v76
	v_lshl_add_u32 v78, v74, 10, v78
	v_lshl_add_u32 v78, v77, 7, v78
	v_lshl_add_u32 v78, v75, 5, v78
	v_sub_co_u32_e32 v80, vcc, v62, v78
	v_subbrev_co_u32_e32 v81, vcc, 0, v63, vcc
	v_readfirstlane_b32 s98, v80
	v_readfirstlane_b32 s99, v81
	v_mul_u32_u24_e32 v79, 0x2100, v76
	v_add_u32_e32 v79, 0x20000, v79
	v_mul_u32_u24_e32 v82, 0x210, v74
	v_lshl_add_u32 v82, v77, 7, v82
	v_lshl_add_u32 v82, v75, 5, v82
	v_add_u32_e32 v86, v79, v82
	v_bfe_u32 v83, v0, 5, 1
	v_lshl_add_u32 v83, v77, 2, v83
	v_and_b32_e32 v84, 31, v0
	v_lshlrev_b32_e32 v84, 4, v84
	v_mul_u32_u24_e32 v85, 0x210, v83
	v_add3_u32 v87, v79, v85, v84
	v_lshl_add_u32 v83, v76, 6, v83
	v_lshl_add_u32 v88, v83, 10, v84
	ds_write_b128 v86, v[174:177]
	ds_write_b128 v86, v[170:173] offset:16
	s_waitcnt lgkmcnt(0)
	s_barrier
	ds_read_b128 v[92:95], v87
	ds_read_b128 v[96:99], v87 offset:1056
	v_add_u32_e32 v89, 0x0, v88
	v_add_u32_e32 v90, 0x800, v88
	s_waitcnt lgkmcnt(1)
	global_store_dwordx4 v89, v[92:95], s[98:99]
	s_waitcnt lgkmcnt(0)
	global_store_dwordx4 v90, v[96:99], s[98:99]
	s_barrier
	ds_write_b128 v86, v[166:169]
	ds_write_b128 v86, v[162:165] offset:16
	s_waitcnt lgkmcnt(0)
	s_barrier
	ds_read_b128 v[92:95], v87
	ds_read_b128 v[96:99], v87 offset:1056
	v_add_u32_e32 v89, 0x200, v88
	v_add_u32_e32 v90, 0xa00, v88
	s_waitcnt lgkmcnt(1)
	global_store_dwordx4 v89, v[92:95], s[98:99]
	s_waitcnt lgkmcnt(0)
	global_store_dwordx4 v90, v[96:99], s[98:99]
	s_barrier
	ds_write_b128 v86, v[158:161]
	ds_write_b128 v86, v[154:157] offset:16
	s_waitcnt lgkmcnt(0)
	s_barrier
	ds_read_b128 v[92:95], v87
	ds_read_b128 v[96:99], v87 offset:1056
	v_add_u32_e32 v89, 0x4000, v88
	v_add_u32_e32 v90, 0x4800, v88
	s_waitcnt lgkmcnt(1)
	global_store_dwordx4 v89, v[92:95], s[98:99]
	s_waitcnt lgkmcnt(0)
	global_store_dwordx4 v90, v[96:99], s[98:99]
	s_barrier
	ds_write_b128 v86, v[150:153]
	ds_write_b128 v86, v[146:149] offset:16
	s_waitcnt lgkmcnt(0)
	s_barrier
	ds_read_b128 v[92:95], v87
	ds_read_b128 v[96:99], v87 offset:1056
	v_add_u32_e32 v89, 0x4200, v88
	v_add_u32_e32 v90, 0x4a00, v88
	s_waitcnt lgkmcnt(1)
	global_store_dwordx4 v89, v[92:95], s[98:99]
	s_waitcnt lgkmcnt(0)
	global_store_dwordx4 v90, v[96:99], s[98:99]
	s_barrier
	ds_write_b128 v86, v[142:145]
	ds_write_b128 v86, v[138:141] offset:16
	s_waitcnt lgkmcnt(0)
	s_barrier
	ds_read_b128 v[92:95], v87
	ds_read_b128 v[96:99], v87 offset:1056
	v_add_u32_e32 v89, 0x8000, v88
	v_add_u32_e32 v90, 0x8800, v88
	s_waitcnt lgkmcnt(1)
	global_store_dwordx4 v89, v[92:95], s[98:99]
	s_waitcnt lgkmcnt(0)
	global_store_dwordx4 v90, v[96:99], s[98:99]
	s_barrier
	ds_write_b128 v86, v[134:137]
	ds_write_b128 v86, v[130:133] offset:16
	s_waitcnt lgkmcnt(0)
	s_barrier
	ds_read_b128 v[92:95], v87
	ds_read_b128 v[96:99], v87 offset:1056
	v_add_u32_e32 v89, 0x8200, v88
	v_add_u32_e32 v90, 0x8a00, v88
	s_waitcnt lgkmcnt(1)
	global_store_dwordx4 v89, v[92:95], s[98:99]
	s_waitcnt lgkmcnt(0)
	global_store_dwordx4 v90, v[96:99], s[98:99]
	s_barrier
	ds_write_b128 v86, v[126:129]
	ds_write_b128 v86, v[122:125] offset:16
	s_waitcnt lgkmcnt(0)
	s_barrier
; template <class Epi, bool ALIGN_EPI = true>
; __device__ __forceinline__ void gemm_phase(LAS unsigned char* lds, const Gemm g, const Order& S, const Epi& E) {
;     ...
;         else {
;             float* sl = g.slab + (size_t)(cur.slot * cur.S + cur.ks) * 65536 + (size_t)(wr * 64 + fr) * 256 + wc * 32 + 8 * fq;
; #pragma unroll
;             for (int ai = 0; ai < 2; ++ai)
; #pragma unroll
;                 for (int m = 0; m < 4; ++m)
; #pragma unroll
;                     for (int bj = 0; bj < 2; ++bj)
; #pragma unroll
;                         for (int n = 0; n < 2; ++n) *(f32x4*)(sl + (size_t)(ai * HALF + m * 16) * 256 + bj * HALF + 4 * n) = acc[ai][bj][m][n];
;         }
	ds_read_b128 v[92:95], v87
	ds_read_b128 v[96:99], v87 offset:1056
	v_add_u32_e32 v89, 0xc000, v88
	v_add_u32_e32 v90, 0xc800, v88
	s_waitcnt lgkmcnt(1)
	global_store_dwordx4 v89, v[92:95], s[98:99]
	s_waitcnt lgkmcnt(0)
	global_store_dwordx4 v90, v[96:99], s[98:99]
	s_barrier
	ds_write_b128 v86, v[118:121]
	ds_write_b128 v86, v[114:117] offset:16
	s_waitcnt lgkmcnt(0)
	s_barrier
	ds_read_b128 v[92:95], v87
	ds_read_b128 v[96:99], v87 offset:1056
	v_add_u32_e32 v89, 0xc200, v88
	v_add_u32_e32 v90, 0xca00, v88
	s_waitcnt lgkmcnt(1)
	global_store_dwordx4 v89, v[92:95], s[98:99]
	s_waitcnt lgkmcnt(0)
	global_store_dwordx4 v90, v[96:99], s[98:99]
	s_barrier
	ds_write_b128 v86, v[70:73]
	ds_write_b128 v86, v[58:61] offset:16
	s_waitcnt lgkmcnt(0)
	s_barrier
	ds_read_b128 v[92:95], v87
	ds_read_b128 v[96:99], v87 offset:1056
	v_add_u32_e32 v89, 0x20000, v88
	v_add_u32_e32 v90, 0x20800, v88
	s_waitcnt lgkmcnt(1)
	global_store_dwordx4 v89, v[92:95], s[98:99]
	s_waitcnt lgkmcnt(0)
	global_store_dwordx4 v90, v[96:99], s[98:99]
	s_barrier
	ds_write_b128 v86, v[54:57]
	ds_write_b128 v86, v[50:53] offset:16
	s_waitcnt lgkmcnt(0)
	s_barrier
	ds_read_b128 v[92:95], v87
	ds_read_b128 v[96:99], v87 offset:1056
	v_add_u32_e32 v89, 0x20200, v88
	v_add_u32_e32 v90, 0x20a00, v88
	s_waitcnt lgkmcnt(1)
	global_store_dwordx4 v89, v[92:95], s[98:99]
	s_waitcnt lgkmcnt(0)
	global_store_dwordx4 v90, v[96:99], s[98:99]
	s_barrier
	ds_write_b128 v86, v[46:49]
	ds_write_b128 v86, v[42:45] offset:16
	s_waitcnt lgkmcnt(0)
	s_barrier
	ds_read_b128 v[92:95], v87
	ds_read_b128 v[96:99], v87 offset:1056
	v_add_u32_e32 v89, 0x24000, v88
	v_add_u32_e32 v90, 0x24800, v88
	s_waitcnt lgkmcnt(1)
	global_store_dwordx4 v89, v[92:95], s[98:99]
	s_waitcnt lgkmcnt(0)
	global_store_dwordx4 v90, v[96:99], s[98:99]
	s_barrier
	ds_write_b128 v86, v[38:41]
	ds_write_b128 v86, v[34:37] offset:16
	s_waitcnt lgkmcnt(0)
	s_barrier
	ds_read_b128 v[92:95], v87
	ds_read_b128 v[96:99], v87 offset:1056
	v_add_u32_e32 v89, 0x24200, v88
	v_add_u32_e32 v90, 0x24a00, v88
	s_waitcnt lgkmcnt(1)
	global_store_dwordx4 v89, v[92:95], s[98:99]
	s_waitcnt lgkmcnt(0)
	global_store_dwordx4 v90, v[96:99], s[98:99]
	s_barrier
	ds_write_b128 v86, v[30:33]
	ds_write_b128 v86, v[26:29] offset:16
	s_waitcnt lgkmcnt(0)
	s_barrier
	ds_read_b128 v[92:95], v87
	ds_read_b128 v[96:99], v87 offset:1056
	v_add_u32_e32 v89, 0x28000, v88
	v_add_u32_e32 v90, 0x28800, v88
	s_waitcnt lgkmcnt(1)
	global_store_dwordx4 v89, v[92:95], s[98:99]
	s_waitcnt lgkmcnt(0)
	global_store_dwordx4 v90, v[96:99], s[98:99]
	s_barrier
	ds_write_b128 v86, v[22:25]
	ds_write_b128 v86, v[18:21] offset:16
	s_waitcnt lgkmcnt(0)
	s_barrier
	ds_read_b128 v[92:95], v87
	ds_read_b128 v[96:99], v87 offset:1056
	v_add_u32_e32 v89, 0x28200, v88
	v_add_u32_e32 v90, 0x28a00, v88
	s_waitcnt lgkmcnt(1)
	global_store_dwordx4 v89, v[92:95], s[98:99]
	s_waitcnt lgkmcnt(0)
	global_store_dwordx4 v90, v[96:99], s[98:99]
	s_barrier
	ds_write_b128 v86, v[14:17]
	ds_write_b128 v86, v[10:13] offset:16
	s_waitcnt lgkmcnt(0)
	s_barrier
	ds_read_b128 v[92:95], v87
	ds_read_b128 v[96:99], v87 offset:1056
	v_add_u32_e32 v89, 0x2c000, v88
	v_add_u32_e32 v90, 0x2c800, v88
	s_waitcnt lgkmcnt(1)
	global_store_dwordx4 v89, v[92:95], s[98:99]
	s_waitcnt lgkmcnt(0)
	global_store_dwordx4 v90, v[96:99], s[98:99]
	s_barrier
	ds_write_b128 v86, v[6:9]
	ds_write_b128 v86, v[2:5] offset:16
	s_waitcnt lgkmcnt(0)
	s_barrier
	ds_read_b128 v[92:95], v87
	ds_read_b128 v[96:99], v87 offset:1056
	v_add_u32_e32 v89, 0x2c200, v88
	v_add_u32_e32 v90, 0x2ca00, v88
	s_waitcnt lgkmcnt(1)
	global_store_dwordx4 v89, v[92:95], s[98:99]
	s_waitcnt lgkmcnt(0)
	global_store_dwordx4 v90, v[96:99], s[98:99]
	s_barrier
	s_mov_b32 s28, 0xc000
	s_mov_b32 s28, 0x20000
	s_mov_b32 s28, 0x24000
	s_cbranch_execnz .LBB0_397
